# GEMM tiles: first K-step pair peeled, the first MFMA into each accumulator takes a zero C operand - the 128 per-tile accumulator zeroing moves are gone
# speedup vs baseline: 1.0116x; 1.0116x over previous
.LBB0_31:
	s_add_u32 s40, s12, 0x100
	s_addc_u32 s41, s13, 0
	s_mov_b32 s42, -2
	s_waitcnt vmcnt(0)
	v_add_u32_e32 v204, 0x10000, v207
	v_add_u32_e32 v205, 0x14000, v207
	v_add_u32_e32 v210, 0x18000, v207
	v_add_u32_e32 v211, 0x1c000, v207
	s_add_u32 s12, s10, 0x100
	s_addc_u32 s13, s11, 0
	s_cmpk_eq_i32 s42, 0x52
	s_cselect_b32 s17, s1, s13
	s_cselect_b32 s16, s0, s12
	s_cselect_b32 s15, s9, s41
	s_cselect_b32 s14, s8, s40
	ds_read_b128 v[130:133], v204
	ds_read_b128 v[134:137], v204 offset:1024
	ds_read_b128 v[138:141], v204 offset:2048
	ds_read_b128 v[142:145], v204 offset:3072
	ds_read_b128 v[146:149], v205
	ds_read_b128 v[150:153], v205 offset:1024
	ds_read_b128 v[154:157], v205 offset:2048
	ds_read_b128 v[158:161], v205 offset:3072
	ds_read_b128 v[162:165], v208
	ds_read_b128 v[166:169], v208 offset:1024
	ds_read_b128 v[170:173], v208 offset:2048
	ds_read_b128 v[184:187], v208 offset:3072
	ds_read_b128 v[188:191], v208 offset:4096
	s_add_i32 m0, s23, 0xc000
	ds_read_b128 v[192:195], v208 offset:5120
	global_load_lds_dwordx4 v180, s[10:11]
	s_add_i32 m0, s23, 0xe000
	ds_read_b128 v[196:199], v208 offset:6144
	global_load_lds_dwordx4 v182, s[10:11]
	ds_read_b128 v[200:203], v208 offset:7168
	s_waitcnt vmcnt(8) lgkmcnt(0)
	s_barrier
	v_mfma_f32_16x16x32_bf16 v[126:129], v[130:133], v[162:165], 0
	v_mfma_f32_16x16x32_bf16 v[94:97], v[138:141], v[162:165], 0
	v_mfma_f32_16x16x32_bf16 v[122:125], v[130:133], v[170:173], 0
	v_mfma_f32_16x16x32_bf16 v[90:93], v[138:141], v[170:173], 0
	v_mfma_f32_16x16x32_bf16 v[118:121], v[130:133], v[188:191], 0
	v_mfma_f32_16x16x32_bf16 v[86:89], v[138:141], v[188:191], 0
	v_mfma_f32_16x16x32_bf16 v[114:117], v[130:133], v[196:199], 0
	v_mfma_f32_16x16x32_bf16 v[82:85], v[138:141], v[196:199], 0
	v_mfma_f32_16x16x32_bf16 v[126:129], v[134:137], v[166:169], v[126:129]
	v_mfma_f32_16x16x32_bf16 v[94:97], v[142:145], v[166:169], v[94:97]
	v_mfma_f32_16x16x32_bf16 v[122:125], v[134:137], v[184:187], v[122:125]
	v_mfma_f32_16x16x32_bf16 v[90:93], v[142:145], v[184:187], v[90:93]
	v_mfma_f32_16x16x32_bf16 v[118:121], v[134:137], v[192:195], v[118:121]
	v_mfma_f32_16x16x32_bf16 v[86:89], v[142:145], v[192:195], v[86:89]
	v_mfma_f32_16x16x32_bf16 v[114:117], v[134:137], v[200:203], v[114:117]
	v_mfma_f32_16x16x32_bf16 v[82:85], v[142:145], v[200:203], v[82:85]
	v_mfma_f32_16x16x32_bf16 v[66:69], v[146:149], v[162:165], 0
	v_mfma_f32_16x16x32_bf16 v[42:45], v[154:157], v[162:165], 0
	v_mfma_f32_16x16x32_bf16 v[58:61], v[146:149], v[170:173], 0
	v_mfma_f32_16x16x32_bf16 v[30:33], v[154:157], v[170:173], 0
	v_mfma_f32_16x16x32_bf16 v[54:57], v[146:149], v[188:191], 0
	v_mfma_f32_16x16x32_bf16 v[22:25], v[154:157], v[188:191], 0
	v_mfma_f32_16x16x32_bf16 v[50:53], v[146:149], v[196:199], 0
	v_mfma_f32_16x16x32_bf16 v[18:21], v[154:157], v[196:199], 0
	v_mfma_f32_16x16x32_bf16 v[66:69], v[150:153], v[166:169], v[66:69]
	v_mfma_f32_16x16x32_bf16 v[42:45], v[158:161], v[166:169], v[42:45]
	v_mfma_f32_16x16x32_bf16 v[58:61], v[150:153], v[184:187], v[58:61]
	v_mfma_f32_16x16x32_bf16 v[30:33], v[158:161], v[184:187], v[30:33]
	v_mfma_f32_16x16x32_bf16 v[54:57], v[150:153], v[192:195], v[54:57]
	v_mfma_f32_16x16x32_bf16 v[22:25], v[158:161], v[192:195], v[22:25]
	v_mfma_f32_16x16x32_bf16 v[50:53], v[150:153], v[200:203], v[50:53]
	v_mfma_f32_16x16x32_bf16 v[18:21], v[158:161], v[200:203], v[18:21]
	s_barrier
	ds_read_b128 v[162:165], v208 offset:16384
	s_add_i32 m0, s22, 0x10000
	ds_read_b128 v[166:169], v208 offset:17408
	global_load_lds_dwordx4 v178, s[14:15]
	s_add_i32 m0, s22, 0x12000
	s_add_u32 s10, s14, 0x158000
	s_addc_u32 s11, s15, 0
	ds_read_b128 v[170:173], v208 offset:18432
	global_load_lds_dwordx4 v176, s[14:15]
	s_add_i32 m0, s22, 0x14000
	ds_read_b128 v[184:187], v208 offset:19456
	global_load_lds_dwordx4 v178, s[10:11]
	s_add_i32 m0, s22, 0x16000
	ds_read_b128 v[188:191], v208 offset:20480
	global_load_lds_dwordx4 v176, s[10:11]
	s_mov_b32 m0, s23
	ds_read_b128 v[192:195], v208 offset:21504
	global_load_lds_dwordx4 v178, s[16:17]
	s_mov_b32 m0, s24
	ds_read_b128 v[196:199], v208 offset:22528
	global_load_lds_dwordx4 v176, s[16:17]
	ds_read_b128 v[200:203], v208 offset:23552
	s_waitcnt vmcnt(8) lgkmcnt(0)
	s_barrier
	v_mfma_f32_16x16x32_bf16 v[110:113], v[130:133], v[162:165], 0
	v_mfma_f32_16x16x32_bf16 v[78:81], v[138:141], v[162:165], 0
	v_mfma_f32_16x16x32_bf16 v[106:109], v[130:133], v[170:173], 0
	v_mfma_f32_16x16x32_bf16 v[74:77], v[138:141], v[170:173], 0
	v_mfma_f32_16x16x32_bf16 v[102:105], v[130:133], v[188:191], 0
	v_mfma_f32_16x16x32_bf16 v[70:73], v[138:141], v[188:191], 0
	v_mfma_f32_16x16x32_bf16 v[98:101], v[130:133], v[196:199], 0
	v_mfma_f32_16x16x32_bf16 v[62:65], v[138:141], v[196:199], 0
	v_mfma_f32_16x16x32_bf16 v[110:113], v[134:137], v[166:169], v[110:113]
	v_mfma_f32_16x16x32_bf16 v[78:81], v[142:145], v[166:169], v[78:81]
	v_mfma_f32_16x16x32_bf16 v[106:109], v[134:137], v[184:187], v[106:109]
	v_mfma_f32_16x16x32_bf16 v[74:77], v[142:145], v[184:187], v[74:77]
	v_mfma_f32_16x16x32_bf16 v[102:105], v[134:137], v[192:195], v[102:105]
	v_mfma_f32_16x16x32_bf16 v[70:73], v[142:145], v[192:195], v[70:73]
	v_mfma_f32_16x16x32_bf16 v[98:101], v[134:137], v[200:203], v[98:101]
	v_mfma_f32_16x16x32_bf16 v[62:65], v[142:145], v[200:203], v[62:65]
	v_mfma_f32_16x16x32_bf16 v[46:49], v[146:149], v[162:165], 0
	v_mfma_f32_16x16x32_bf16 v[12:15], v[154:157], v[162:165], 0
	v_mfma_f32_16x16x32_bf16 v[38:41], v[146:149], v[170:173], 0
	v_mfma_f32_16x16x32_bf16 v[8:11], v[154:157], v[170:173], 0
	v_mfma_f32_16x16x32_bf16 v[34:37], v[146:149], v[188:191], 0
	v_mfma_f32_16x16x32_bf16 v[4:7], v[154:157], v[188:191], 0
	v_mfma_f32_16x16x32_bf16 v[26:29], v[146:149], v[196:199], 0
	v_mfma_f32_16x16x32_bf16 v[0:3], v[154:157], v[196:199], 0
	v_mfma_f32_16x16x32_bf16 v[46:49], v[150:153], v[166:169], v[46:49]
	v_mfma_f32_16x16x32_bf16 v[12:15], v[158:161], v[166:169], v[12:15]
	v_mfma_f32_16x16x32_bf16 v[38:41], v[150:153], v[184:187], v[38:41]
	v_mfma_f32_16x16x32_bf16 v[8:11], v[158:161], v[184:187], v[8:11]
	v_mfma_f32_16x16x32_bf16 v[34:37], v[150:153], v[192:195], v[34:37]
	v_mfma_f32_16x16x32_bf16 v[4:7], v[158:161], v[192:195], v[4:7]
	v_mfma_f32_16x16x32_bf16 v[26:29], v[150:153], v[200:203], v[26:29]
	v_mfma_f32_16x16x32_bf16 v[0:3], v[158:161], v[200:203], v[0:3]
	s_barrier
	s_add_u32 s100, s16, 0x158000
	s_addc_u32 s101, s17, 0
	ds_read_b128 v[130:133], v210
	ds_read_b128 v[134:137], v210 offset:1024
	ds_read_b128 v[138:141], v210 offset:2048
	ds_read_b128 v[142:145], v210 offset:3072
	ds_read_b128 v[146:149], v211
	ds_read_b128 v[150:153], v211 offset:1024
	ds_read_b128 v[154:157], v211 offset:2048
	ds_read_b128 v[158:161], v211 offset:3072
	ds_read_b128 v[162:165], v208 offset:32768
	ds_read_b128 v[166:169], v208 offset:33792
	ds_read_b128 v[170:173], v208 offset:34816
	ds_read_b128 v[184:187], v208 offset:35840
	ds_read_b128 v[188:191], v208 offset:36864
	s_mov_b32 m0, s25
	ds_read_b128 v[192:195], v208 offset:37888
	global_load_lds_dwordx4 v178, s[100:101]
	s_mov_b32 m0, s26
	ds_read_b128 v[196:199], v208 offset:38912
	global_load_lds_dwordx4 v176, s[100:101]
	ds_read_b128 v[200:203], v208 offset:39936
	s_waitcnt vmcnt(8) lgkmcnt(0)
	s_barrier
	v_mfma_f32_16x16x32_bf16 v[126:129], v[130:133], v[162:165], v[126:129]
	v_mfma_f32_16x16x32_bf16 v[94:97], v[138:141], v[162:165], v[94:97]
	v_mfma_f32_16x16x32_bf16 v[122:125], v[130:133], v[170:173], v[122:125]
	v_mfma_f32_16x16x32_bf16 v[90:93], v[138:141], v[170:173], v[90:93]
	v_mfma_f32_16x16x32_bf16 v[118:121], v[130:133], v[188:191], v[118:121]
	v_mfma_f32_16x16x32_bf16 v[86:89], v[138:141], v[188:191], v[86:89]
	v_mfma_f32_16x16x32_bf16 v[114:117], v[130:133], v[196:199], v[114:117]
	v_mfma_f32_16x16x32_bf16 v[82:85], v[138:141], v[196:199], v[82:85]
	v_mfma_f32_16x16x32_bf16 v[126:129], v[134:137], v[166:169], v[126:129]
	v_mfma_f32_16x16x32_bf16 v[94:97], v[142:145], v[166:169], v[94:97]
	v_mfma_f32_16x16x32_bf16 v[122:125], v[134:137], v[184:187], v[122:125]
	v_mfma_f32_16x16x32_bf16 v[90:93], v[142:145], v[184:187], v[90:93]
	v_mfma_f32_16x16x32_bf16 v[118:121], v[134:137], v[192:195], v[118:121]
	v_mfma_f32_16x16x32_bf16 v[86:89], v[142:145], v[192:195], v[86:89]
	v_mfma_f32_16x16x32_bf16 v[114:117], v[134:137], v[200:203], v[114:117]
	v_mfma_f32_16x16x32_bf16 v[82:85], v[142:145], v[200:203], v[82:85]
	v_mfma_f32_16x16x32_bf16 v[66:69], v[146:149], v[162:165], v[66:69]
	v_mfma_f32_16x16x32_bf16 v[42:45], v[154:157], v[162:165], v[42:45]
	v_mfma_f32_16x16x32_bf16 v[58:61], v[146:149], v[170:173], v[58:61]
	v_mfma_f32_16x16x32_bf16 v[30:33], v[154:157], v[170:173], v[30:33]
	v_mfma_f32_16x16x32_bf16 v[54:57], v[146:149], v[188:191], v[54:57]
	v_mfma_f32_16x16x32_bf16 v[22:25], v[154:157], v[188:191], v[22:25]
	v_mfma_f32_16x16x32_bf16 v[50:53], v[146:149], v[196:199], v[50:53]
	v_mfma_f32_16x16x32_bf16 v[18:21], v[154:157], v[196:199], v[18:21]
	v_mfma_f32_16x16x32_bf16 v[66:69], v[150:153], v[166:169], v[66:69]
	v_mfma_f32_16x16x32_bf16 v[42:45], v[158:161], v[166:169], v[42:45]
	v_mfma_f32_16x16x32_bf16 v[58:61], v[150:153], v[184:187], v[58:61]
	v_mfma_f32_16x16x32_bf16 v[30:33], v[158:161], v[184:187], v[30:33]
	v_mfma_f32_16x16x32_bf16 v[54:57], v[150:153], v[192:195], v[54:57]
	v_mfma_f32_16x16x32_bf16 v[22:25], v[158:161], v[192:195], v[22:25]
	v_mfma_f32_16x16x32_bf16 v[50:53], v[150:153], v[200:203], v[50:53]
	v_mfma_f32_16x16x32_bf16 v[18:21], v[158:161], v[200:203], v[18:21]
	s_barrier
	ds_read_b128 v[162:165], v208 offset:49152
	s_add_i32 m0, s22, 0x17f80
	ds_read_b128 v[166:169], v208 offset:50176
	global_load_lds_dwordx4 v178, s[14:15] offset:128
	s_add_i32 m0, s22, 0x19f80
	ds_read_b128 v[170:173], v208 offset:51200
	global_load_lds_dwordx4 v176, s[14:15] offset:128
	s_add_i32 m0, s22, 0x1bf80
	ds_read_b128 v[184:187], v208 offset:52224
	global_load_lds_dwordx4 v178, s[10:11] offset:128
	s_add_i32 m0, s22, 0x1df80
	ds_read_b128 v[188:191], v208 offset:53248
	global_load_lds_dwordx4 v176, s[10:11] offset:128
	s_add_i32 m0, s31, 0xffffff80
	ds_read_b128 v[192:195], v208 offset:54272
	global_load_lds_dwordx4 v178, s[16:17] offset:128
	s_add_i32 m0, s34, 0xffffff80
	ds_read_b128 v[196:199], v208 offset:55296
	global_load_lds_dwordx4 v176, s[16:17] offset:128
	ds_read_b128 v[200:203], v208 offset:56320
	s_waitcnt vmcnt(8) lgkmcnt(0)
	s_barrier
	v_mfma_f32_16x16x32_bf16 v[110:113], v[130:133], v[162:165], v[110:113]
	v_mfma_f32_16x16x32_bf16 v[78:81], v[138:141], v[162:165], v[78:81]
	v_mfma_f32_16x16x32_bf16 v[106:109], v[130:133], v[170:173], v[106:109]
	v_mfma_f32_16x16x32_bf16 v[74:77], v[138:141], v[170:173], v[74:77]
	v_mfma_f32_16x16x32_bf16 v[102:105], v[130:133], v[188:191], v[102:105]
	v_mfma_f32_16x16x32_bf16 v[70:73], v[138:141], v[188:191], v[70:73]
	v_mfma_f32_16x16x32_bf16 v[98:101], v[130:133], v[196:199], v[98:101]
	v_mfma_f32_16x16x32_bf16 v[62:65], v[138:141], v[196:199], v[62:65]
	v_mfma_f32_16x16x32_bf16 v[110:113], v[134:137], v[166:169], v[110:113]
	v_mfma_f32_16x16x32_bf16 v[78:81], v[142:145], v[166:169], v[78:81]
	v_mfma_f32_16x16x32_bf16 v[106:109], v[134:137], v[184:187], v[106:109]
	v_mfma_f32_16x16x32_bf16 v[74:77], v[142:145], v[184:187], v[74:77]
	v_mfma_f32_16x16x32_bf16 v[102:105], v[134:137], v[192:195], v[102:105]
	v_mfma_f32_16x16x32_bf16 v[70:73], v[142:145], v[192:195], v[70:73]
	v_mfma_f32_16x16x32_bf16 v[98:101], v[134:137], v[200:203], v[98:101]
	v_mfma_f32_16x16x32_bf16 v[62:65], v[142:145], v[200:203], v[62:65]
	v_mfma_f32_16x16x32_bf16 v[46:49], v[146:149], v[162:165], v[46:49]
	v_mfma_f32_16x16x32_bf16 v[12:15], v[154:157], v[162:165], v[12:15]
	v_mfma_f32_16x16x32_bf16 v[38:41], v[146:149], v[170:173], v[38:41]
	v_mfma_f32_16x16x32_bf16 v[8:11], v[154:157], v[170:173], v[8:11]
	v_mfma_f32_16x16x32_bf16 v[34:37], v[146:149], v[188:191], v[34:37]
	v_mfma_f32_16x16x32_bf16 v[4:7], v[154:157], v[188:191], v[4:7]
	v_mfma_f32_16x16x32_bf16 v[26:29], v[146:149], v[196:199], v[26:29]
	v_mfma_f32_16x16x32_bf16 v[0:3], v[154:157], v[196:199], v[0:3]
	v_mfma_f32_16x16x32_bf16 v[46:49], v[150:153], v[166:169], v[46:49]
	v_mfma_f32_16x16x32_bf16 v[12:15], v[158:161], v[166:169], v[12:15]
	v_mfma_f32_16x16x32_bf16 v[38:41], v[150:153], v[184:187], v[38:41]
	v_mfma_f32_16x16x32_bf16 v[8:11], v[158:161], v[184:187], v[8:11]
	v_mfma_f32_16x16x32_bf16 v[34:37], v[150:153], v[192:195], v[34:37]
	v_mfma_f32_16x16x32_bf16 v[4:7], v[158:161], v[192:195], v[4:7]
	v_mfma_f32_16x16x32_bf16 v[26:29], v[150:153], v[200:203], v[26:29]
	v_mfma_f32_16x16x32_bf16 v[0:3], v[158:161], v[200:203], v[0:3]
	s_barrier
	s_add_i32 s42, s42, 2
	s_add_u32 s40, s40, 0x100
	s_addc_u32 s41, s41, 0
	s_mov_b64 s[10:11], s[12:13]

.LBB0_67:
	s_ashr_i32 s21, s20, 31
	s_lshl_b64 s[10:11], s[20:21], 20
	s_add_u32 s22, s34, s10
	s_addc_u32 s23, s35, s11
	s_and_b64 s[10:11], s[4:5], exec
	s_cselect_b32 s21, s23, s7
	s_cselect_b32 s28, s22, s6
	s_ashr_i32 s19, s18, 31
	s_lshl_b64 s[10:11], s[18:19], 20
	s_add_u32 s24, s36, s10
	s_addc_u32 s25, s37, s11
	s_and_b64 s[10:11], s[4:5], exec
	s_cselect_b32 s19, s25, s9
	s_cselect_b32 s29, s24, s8
	s_add_u32 s6, s6, 0x80080
	s_addc_u32 s7, s7, 0
	s_add_u32 s30, s8, 0x100
	s_addc_u32 s31, s9, 0
	s_mov_b32 s51, -2
	s_waitcnt vmcnt(0)
	v_add_u32_e32 v214, 0x10000, v190
	v_add_u32_e32 v215, 0x14000, v190
	v_add_u32_e32 v234, 0x18000, v190
	v_add_u32_e32 v235, 0x1c000, v190
	s_add_u32 s8, s6, 0xfff80080
	s_addc_u32 s9, s7, -1
	s_cmp_eq_u32 s51, 28
	s_cselect_b32 s11, s21, s9
	s_cselect_b32 s10, s28, s8
	s_cselect_b32 s9, s19, s31
	s_cselect_b32 s8, s29, s30
	ds_read_b128 v[54:57], v214
	ds_read_b128 v[62:65], v214 offset:1024
	ds_read_b128 v[66:69], v214 offset:2048
	ds_read_b128 v[70:73], v214 offset:3072
	ds_read_b128 v[74:77], v215
	ds_read_b128 v[78:81], v215 offset:1024
	ds_read_b128 v[82:85], v215 offset:2048
	ds_read_b128 v[86:89], v215 offset:3072
	ds_read_b128 v[170:173], v192
	ds_read_b128 v[184:187], v192 offset:1024
	ds_read_b128 v[194:197], v192 offset:2048
	ds_read_b128 v[198:201], v192 offset:3072
	ds_read_b128 v[202:205], v192 offset:4096
	s_add_i32 m0, s41, 0xc000
	ds_read_b128 v[206:209], v192 offset:5120
	global_load_lds_dwordx4 v180, s[6:7]
	s_add_i32 m0, s41, 0xe000
	ds_read_b128 v[210:213], v192 offset:6144
	global_load_lds_dwordx4 v182, s[6:7]
	ds_read_b128 v[222:225], v192 offset:7168
	s_waitcnt vmcnt(8) lgkmcnt(0)
	s_barrier
	v_mfma_f32_16x16x32_bf16 v[150:153], v[54:57], v[170:173], 0
	v_mfma_f32_16x16x32_bf16 v[142:145], v[66:69], v[170:173], 0
	v_mfma_f32_16x16x32_bf16 v[134:137], v[54:57], v[194:197], 0
	v_mfma_f32_16x16x32_bf16 v[126:129], v[66:69], v[194:197], 0
	v_mfma_f32_16x16x32_bf16 v[118:121], v[54:57], v[202:205], 0
	v_mfma_f32_16x16x32_bf16 v[114:117], v[66:69], v[202:205], 0
	v_mfma_f32_16x16x32_bf16 v[110:113], v[54:57], v[210:213], 0
	v_mfma_f32_16x16x32_bf16 v[106:109], v[66:69], v[210:213], 0
	v_mfma_f32_16x16x32_bf16 v[150:153], v[62:65], v[184:187], v[150:153]
	v_mfma_f32_16x16x32_bf16 v[142:145], v[70:73], v[184:187], v[142:145]
	v_mfma_f32_16x16x32_bf16 v[134:137], v[62:65], v[198:201], v[134:137]
	v_mfma_f32_16x16x32_bf16 v[126:129], v[70:73], v[198:201], v[126:129]
	v_mfma_f32_16x16x32_bf16 v[118:121], v[62:65], v[206:209], v[118:121]
	v_mfma_f32_16x16x32_bf16 v[114:117], v[70:73], v[206:209], v[114:117]
	v_mfma_f32_16x16x32_bf16 v[110:113], v[62:65], v[222:225], v[110:113]
	v_mfma_f32_16x16x32_bf16 v[106:109], v[70:73], v[222:225], v[106:109]
	v_mfma_f32_16x16x32_bf16 v[158:161], v[74:77], v[170:173], 0
	v_mfma_f32_16x16x32_bf16 v[154:157], v[82:85], v[170:173], 0
	v_mfma_f32_16x16x32_bf16 v[146:149], v[74:77], v[194:197], 0
	v_mfma_f32_16x16x32_bf16 v[138:141], v[82:85], v[194:197], 0
	v_mfma_f32_16x16x32_bf16 v[130:133], v[74:77], v[202:205], 0
	v_mfma_f32_16x16x32_bf16 v[122:125], v[82:85], v[202:205], 0
	v_mfma_f32_16x16x32_bf16 v[102:105], v[74:77], v[210:213], 0
	v_mfma_f32_16x16x32_bf16 v[98:101], v[82:85], v[210:213], 0
	v_mfma_f32_16x16x32_bf16 v[158:161], v[78:81], v[184:187], v[158:161]
	v_mfma_f32_16x16x32_bf16 v[154:157], v[86:89], v[184:187], v[154:157]
	v_mfma_f32_16x16x32_bf16 v[146:149], v[78:81], v[198:201], v[146:149]
	v_mfma_f32_16x16x32_bf16 v[138:141], v[86:89], v[198:201], v[138:141]
	v_mfma_f32_16x16x32_bf16 v[130:133], v[78:81], v[206:209], v[130:133]
	v_mfma_f32_16x16x32_bf16 v[122:125], v[86:89], v[206:209], v[122:125]
	v_mfma_f32_16x16x32_bf16 v[102:105], v[78:81], v[222:225], v[102:105]
	v_mfma_f32_16x16x32_bf16 v[98:101], v[86:89], v[222:225], v[98:101]
	s_barrier
	ds_read_b128 v[170:173], v192 offset:16384
	s_add_i32 m0, s38, 0x10000
	ds_read_b128 v[184:187], v192 offset:17408
	global_load_lds_dwordx4 v166, s[8:9]
	s_add_i32 m0, s38, 0x12000
	s_add_u32 s52, s8, 0x80000
	s_addc_u32 s53, s9, 0
	ds_read_b128 v[194:197], v192 offset:18432
	global_load_lds_dwordx4 v162, s[8:9]
	s_add_i32 m0, s38, 0x14000
	ds_read_b128 v[198:201], v192 offset:19456
	global_load_lds_dwordx4 v166, s[52:53]
	s_add_i32 m0, s38, 0x16000
	ds_read_b128 v[202:205], v192 offset:20480
	global_load_lds_dwordx4 v162, s[52:53]
	s_mov_b32 m0, s41
	ds_read_b128 v[206:209], v192 offset:21504
	global_load_lds_dwordx4 v168, s[10:11]
	s_mov_b32 m0, s42
	ds_read_b128 v[210:213], v192 offset:22528
	global_load_lds_dwordx4 v164, s[10:11]
	ds_read_b128 v[222:225], v192 offset:23552
	s_waitcnt vmcnt(8) lgkmcnt(0)
	s_barrier
	v_mfma_f32_16x16x32_bf16 v[58:61], v[54:57], v[170:173], 0
	v_mfma_f32_16x16x32_bf16 v[46:49], v[66:69], v[170:173], 0
	v_mfma_f32_16x16x32_bf16 v[38:41], v[54:57], v[194:197], 0
	v_mfma_f32_16x16x32_bf16 v[30:33], v[66:69], v[194:197], 0
	v_mfma_f32_16x16x32_bf16 v[22:25], v[54:57], v[202:205], 0
	v_mfma_f32_16x16x32_bf16 v[18:21], v[66:69], v[202:205], 0
	v_mfma_f32_16x16x32_bf16 v[8:11], v[54:57], v[210:213], 0
	v_mfma_f32_16x16x32_bf16 v[12:15], v[66:69], v[210:213], 0
	v_mfma_f32_16x16x32_bf16 v[58:61], v[62:65], v[184:187], v[58:61]
	v_mfma_f32_16x16x32_bf16 v[46:49], v[70:73], v[184:187], v[46:49]
	v_mfma_f32_16x16x32_bf16 v[38:41], v[62:65], v[198:201], v[38:41]
	v_mfma_f32_16x16x32_bf16 v[30:33], v[70:73], v[198:201], v[30:33]
	v_mfma_f32_16x16x32_bf16 v[22:25], v[62:65], v[206:209], v[22:25]
	v_mfma_f32_16x16x32_bf16 v[18:21], v[70:73], v[206:209], v[18:21]
	v_mfma_f32_16x16x32_bf16 v[8:11], v[62:65], v[222:225], v[8:11]
	v_mfma_f32_16x16x32_bf16 v[12:15], v[70:73], v[222:225], v[12:15]
	v_mfma_f32_16x16x32_bf16 v[50:53], v[74:77], v[194:197], 0
	v_mfma_f32_16x16x32_bf16 v[42:45], v[82:85], v[194:197], 0
	v_mfma_f32_16x16x32_bf16 v[34:37], v[74:77], v[202:205], 0
	v_mfma_f32_16x16x32_bf16 v[26:29], v[82:85], v[202:205], 0
	v_mfma_f32_16x16x32_bf16 v[0:3], v[74:77], v[210:213], 0
	v_mfma_f32_16x16x32_bf16 v[4:7], v[82:85], v[210:213], 0
	v_mfma_f32_16x16x32_bf16 v[54:57], v[74:77], v[170:173], 0
	v_mfma_f32_16x16x32_bf16 v[62:65], v[82:85], v[170:173], 0
	v_mfma_f32_16x16x32_bf16 v[50:53], v[78:81], v[198:201], v[50:53]
	v_mfma_f32_16x16x32_bf16 v[42:45], v[86:89], v[198:201], v[42:45]
	v_mfma_f32_16x16x32_bf16 v[34:37], v[78:81], v[206:209], v[34:37]
	v_mfma_f32_16x16x32_bf16 v[26:29], v[86:89], v[206:209], v[26:29]
	v_mfma_f32_16x16x32_bf16 v[0:3], v[78:81], v[222:225], v[0:3]
	v_mfma_f32_16x16x32_bf16 v[4:7], v[86:89], v[222:225], v[4:7]
	v_mfma_f32_16x16x32_bf16 v[54:57], v[78:81], v[184:187], v[54:57]
	v_mfma_f32_16x16x32_bf16 v[62:65], v[86:89], v[184:187], v[62:65]
	s_barrier
	s_add_u32 s100, s10, 0x80000
	s_addc_u32 s101, s11, 0
	ds_read_b128 v[66:69], v234
	ds_read_b128 v[70:73], v234 offset:1024
	ds_read_b128 v[74:77], v234 offset:2048
	ds_read_b128 v[78:81], v234 offset:3072
	ds_read_b128 v[82:85], v235
	ds_read_b128 v[86:89], v235 offset:1024
	ds_read_b128 v[170:173], v235 offset:2048
	ds_read_b128 v[184:187], v235 offset:3072
	ds_read_b128 v[90:93], v192 offset:32768
	ds_read_b128 v[94:97], v192 offset:33792
	ds_read_b128 v[194:197], v192 offset:34816
	ds_read_b128 v[198:201], v192 offset:35840
	ds_read_b128 v[202:205], v192 offset:36864
	s_mov_b32 m0, s43
	ds_read_b128 v[206:209], v192 offset:37888
	global_load_lds_dwordx4 v168, s[100:101]
	s_mov_b32 m0, s44
	ds_read_b128 v[210:213], v192 offset:38912
	global_load_lds_dwordx4 v164, s[100:101]
	ds_read_b128 v[222:225], v192 offset:39936
	s_waitcnt vmcnt(8) lgkmcnt(0)
	s_barrier
	v_mfma_f32_16x16x32_bf16 v[150:153], v[66:69], v[90:93], v[150:153]
	v_mfma_f32_16x16x32_bf16 v[142:145], v[74:77], v[90:93], v[142:145]
	v_mfma_f32_16x16x32_bf16 v[134:137], v[66:69], v[194:197], v[134:137]
	v_mfma_f32_16x16x32_bf16 v[126:129], v[74:77], v[194:197], v[126:129]
	v_mfma_f32_16x16x32_bf16 v[118:121], v[66:69], v[202:205], v[118:121]
	v_mfma_f32_16x16x32_bf16 v[114:117], v[74:77], v[202:205], v[114:117]
	v_mfma_f32_16x16x32_bf16 v[110:113], v[66:69], v[210:213], v[110:113]
	v_mfma_f32_16x16x32_bf16 v[106:109], v[74:77], v[210:213], v[106:109]
	v_mfma_f32_16x16x32_bf16 v[150:153], v[70:73], v[94:97], v[150:153]
	v_mfma_f32_16x16x32_bf16 v[142:145], v[78:81], v[94:97], v[142:145]
	v_mfma_f32_16x16x32_bf16 v[134:137], v[70:73], v[198:201], v[134:137]
	v_mfma_f32_16x16x32_bf16 v[126:129], v[78:81], v[198:201], v[126:129]
	v_mfma_f32_16x16x32_bf16 v[118:121], v[70:73], v[206:209], v[118:121]
	v_mfma_f32_16x16x32_bf16 v[114:117], v[78:81], v[206:209], v[114:117]
	v_mfma_f32_16x16x32_bf16 v[110:113], v[70:73], v[222:225], v[110:113]
	v_mfma_f32_16x16x32_bf16 v[106:109], v[78:81], v[222:225], v[106:109]
	v_mfma_f32_16x16x32_bf16 v[158:161], v[82:85], v[90:93], v[158:161]
	v_mfma_f32_16x16x32_bf16 v[90:93], v[170:173], v[90:93], v[154:157]
	v_mfma_f32_16x16x32_bf16 v[154:157], v[184:187], v[94:97], v[90:93]
	v_mfma_f32_16x16x32_bf16 v[90:93], v[82:85], v[194:197], v[146:149]
	v_mfma_f32_16x16x32_bf16 v[146:149], v[86:89], v[198:201], v[90:93]
	v_mfma_f32_16x16x32_bf16 v[90:93], v[170:173], v[194:197], v[138:141]
	v_mfma_f32_16x16x32_bf16 v[138:141], v[184:187], v[198:201], v[90:93]
	v_mfma_f32_16x16x32_bf16 v[90:93], v[82:85], v[202:205], v[130:133]
	v_mfma_f32_16x16x32_bf16 v[130:133], v[86:89], v[206:209], v[90:93]
	v_mfma_f32_16x16x32_bf16 v[90:93], v[170:173], v[202:205], v[122:125]
	v_mfma_f32_16x16x32_bf16 v[122:125], v[184:187], v[206:209], v[90:93]
	v_mfma_f32_16x16x32_bf16 v[90:93], v[82:85], v[210:213], v[102:105]
	v_mfma_f32_16x16x32_bf16 v[102:105], v[86:89], v[222:225], v[90:93]
	v_mfma_f32_16x16x32_bf16 v[90:93], v[170:173], v[210:213], v[98:101]
	v_mfma_f32_16x16x32_bf16 v[158:161], v[86:89], v[94:97], v[158:161]
	v_mfma_f32_16x16x32_bf16 v[98:101], v[184:187], v[222:225], v[90:93]
	s_barrier
	ds_read_b128 v[90:93], v192 offset:49152
	s_add_i32 m0, s38, 0x17f80
	ds_read_b128 v[194:197], v192 offset:50176
	global_load_lds_dwordx4 v166, s[8:9] offset:128
	s_add_i32 m0, s38, 0x19f80
	ds_read_b128 v[198:201], v192 offset:51200
	global_load_lds_dwordx4 v162, s[8:9] offset:128
	s_add_i32 m0, s38, 0x1bf80
	ds_read_b128 v[202:205], v192 offset:52224
	global_load_lds_dwordx4 v166, s[52:53] offset:128
	s_add_i32 m0, s38, 0x1df80
	ds_read_b128 v[206:209], v192 offset:53248
	global_load_lds_dwordx4 v162, s[52:53] offset:128
	s_add_i32 m0, s46, 0xffffff80
	ds_read_b128 v[210:213], v192 offset:54272
	global_load_lds_dwordx4 v168, s[10:11] offset:128
	s_add_i32 m0, s47, 0xffffff80
	ds_read_b128 v[222:225], v192 offset:55296
	global_load_lds_dwordx4 v164, s[10:11] offset:128
	ds_read_b128 v[230:233], v192 offset:56320
	s_waitcnt vmcnt(8) lgkmcnt(0)
	s_barrier
	v_mfma_f32_16x16x32_bf16 v[58:61], v[66:69], v[90:93], v[58:61]
	v_mfma_f32_16x16x32_bf16 v[46:49], v[74:77], v[90:93], v[46:49]
	v_mfma_f32_16x16x32_bf16 v[38:41], v[66:69], v[198:201], v[38:41]
	v_mfma_f32_16x16x32_bf16 v[30:33], v[74:77], v[198:201], v[30:33]
	v_mfma_f32_16x16x32_bf16 v[22:25], v[66:69], v[206:209], v[22:25]
	v_mfma_f32_16x16x32_bf16 v[18:21], v[74:77], v[206:209], v[18:21]
	v_mfma_f32_16x16x32_bf16 v[8:11], v[66:69], v[222:225], v[8:11]
	v_mfma_f32_16x16x32_bf16 v[12:15], v[74:77], v[222:225], v[12:15]
	v_mfma_f32_16x16x32_bf16 v[58:61], v[70:73], v[194:197], v[58:61]
	v_mfma_f32_16x16x32_bf16 v[46:49], v[78:81], v[194:197], v[46:49]
	v_mfma_f32_16x16x32_bf16 v[38:41], v[70:73], v[202:205], v[38:41]
	v_mfma_f32_16x16x32_bf16 v[30:33], v[78:81], v[202:205], v[30:33]
	v_mfma_f32_16x16x32_bf16 v[22:25], v[70:73], v[210:213], v[22:25]
	v_mfma_f32_16x16x32_bf16 v[18:21], v[78:81], v[210:213], v[18:21]
	v_mfma_f32_16x16x32_bf16 v[8:11], v[70:73], v[230:233], v[8:11]
	v_mfma_f32_16x16x32_bf16 v[12:15], v[78:81], v[230:233], v[12:15]
	v_mfma_f32_16x16x32_bf16 v[54:57], v[82:85], v[90:93], v[54:57]
	v_mfma_f32_16x16x32_bf16 v[94:97], v[86:89], v[194:197], v[54:57]
	v_mfma_f32_16x16x32_bf16 v[54:57], v[170:173], v[90:93], v[62:65]
	v_mfma_f32_16x16x32_bf16 v[50:53], v[82:85], v[198:201], v[50:53]
	v_mfma_f32_16x16x32_bf16 v[42:45], v[170:173], v[198:201], v[42:45]
	v_mfma_f32_16x16x32_bf16 v[34:37], v[82:85], v[206:209], v[34:37]
	v_mfma_f32_16x16x32_bf16 v[26:29], v[170:173], v[206:209], v[26:29]
	v_mfma_f32_16x16x32_bf16 v[0:3], v[82:85], v[222:225], v[0:3]
	v_mfma_f32_16x16x32_bf16 v[4:7], v[170:173], v[222:225], v[4:7]
	v_mfma_f32_16x16x32_bf16 v[90:93], v[184:187], v[194:197], v[54:57]
	v_mfma_f32_16x16x32_bf16 v[50:53], v[86:89], v[202:205], v[50:53]
	v_mfma_f32_16x16x32_bf16 v[42:45], v[184:187], v[202:205], v[42:45]
	v_mfma_f32_16x16x32_bf16 v[34:37], v[86:89], v[210:213], v[34:37]
	v_mfma_f32_16x16x32_bf16 v[26:29], v[184:187], v[210:213], v[26:29]
	v_mfma_f32_16x16x32_bf16 v[0:3], v[86:89], v[230:233], v[0:3]
	v_mfma_f32_16x16x32_bf16 v[4:7], v[184:187], v[230:233], v[4:7]
	s_barrier
	s_add_i32 s51, s51, 2
	s_add_u32 s6, s6, 0x100
	s_addc_u32 s7, s7, 0
	s_add_u32 s30, s30, 0x100
	s_addc_u32 s31, s31, 0

.LBB0_107:
	s_ashr_i32 s9, s8, 31
	s_lshl_b64 s[10:11], s[8:9], 20
	s_add_u32 s10, s20, s10
	s_addc_u32 s11, s21, s11
	s_and_b64 s[12:13], s[4:5], exec
	s_cselect_b32 s9, s11, s15
	s_cselect_b32 s40, s10, s14
	s_ashr_i32 s7, s6, 31
	s_lshl_b64 s[12:13], s[6:7], 20
	s_add_u32 s12, s22, s12
	s_addc_u32 s13, s23, s13
	s_and_b64 s[18:19], s[4:5], exec
	s_cselect_b32 s7, s13, s17
	s_cselect_b32 s41, s12, s16
	s_add_u32 s14, s14, 0x80080
	s_addc_u32 s15, s15, 0
	s_add_u32 s42, s16, 0x100
	s_addc_u32 s43, s17, 0
	s_mov_b32 s44, -2
	s_waitcnt vmcnt(0)
	v_add_u32_e32 v170, 0x10000, v207
	v_add_u32_e32 v171, 0x14000, v207
	v_add_u32_e32 v172, 0x18000, v207
	v_add_u32_e32 v173, 0x1c000, v207
	s_add_u32 s16, s14, 0xfff80080
	s_addc_u32 s17, s15, -1
	s_cmp_eq_u32 s44, 28
	s_cselect_b32 s19, s9, s17
	s_cselect_b32 s18, s40, s16
	s_cselect_b32 s17, s7, s43
	s_cselect_b32 s16, s41, s42
	ds_read_b128 v[130:133], v170
	ds_read_b128 v[134:137], v170 offset:1024
	ds_read_b128 v[138:141], v170 offset:2048
	ds_read_b128 v[142:145], v170 offset:3072
	ds_read_b128 v[146:149], v171
	ds_read_b128 v[150:153], v171 offset:1024
	ds_read_b128 v[154:157], v171 offset:2048
	ds_read_b128 v[158:161], v171 offset:3072
	ds_read_b128 v[162:165], v208
	ds_read_b128 v[166:169], v208 offset:1024
	ds_read_b128 v[184:187], v208 offset:2048
	ds_read_b128 v[188:191], v208 offset:3072
	ds_read_b128 v[192:195], v208 offset:4096
	s_add_i32 m0, s25, 0xc000
	ds_read_b128 v[196:199], v208 offset:5120
	global_load_lds_dwordx4 v180, s[14:15]
	s_add_i32 m0, s25, 0xe000
	ds_read_b128 v[200:203], v208 offset:6144
	global_load_lds_dwordx4 v182, s[14:15]
	ds_read_b128 v[210:213], v208 offset:7168
	s_waitcnt vmcnt(8) lgkmcnt(0)
	s_barrier
	v_mfma_f32_16x16x32_bf16 v[126:129], v[130:133], v[162:165], 0
	v_mfma_f32_16x16x32_bf16 v[94:97], v[138:141], v[162:165], 0
	v_mfma_f32_16x16x32_bf16 v[122:125], v[130:133], v[184:187], 0
	v_mfma_f32_16x16x32_bf16 v[90:93], v[138:141], v[184:187], 0
	v_mfma_f32_16x16x32_bf16 v[118:121], v[130:133], v[192:195], 0
	v_mfma_f32_16x16x32_bf16 v[86:89], v[138:141], v[192:195], 0
	v_mfma_f32_16x16x32_bf16 v[114:117], v[130:133], v[200:203], 0
	v_mfma_f32_16x16x32_bf16 v[82:85], v[138:141], v[200:203], 0
	v_mfma_f32_16x16x32_bf16 v[126:129], v[134:137], v[166:169], v[126:129]
	v_mfma_f32_16x16x32_bf16 v[94:97], v[142:145], v[166:169], v[94:97]
	v_mfma_f32_16x16x32_bf16 v[122:125], v[134:137], v[188:191], v[122:125]
	v_mfma_f32_16x16x32_bf16 v[90:93], v[142:145], v[188:191], v[90:93]
	v_mfma_f32_16x16x32_bf16 v[118:121], v[134:137], v[196:199], v[118:121]
	v_mfma_f32_16x16x32_bf16 v[86:89], v[142:145], v[196:199], v[86:89]
	v_mfma_f32_16x16x32_bf16 v[114:117], v[134:137], v[210:213], v[114:117]
	v_mfma_f32_16x16x32_bf16 v[82:85], v[142:145], v[210:213], v[82:85]
	v_mfma_f32_16x16x32_bf16 v[66:69], v[146:149], v[162:165], 0
	v_mfma_f32_16x16x32_bf16 v[42:45], v[154:157], v[162:165], 0
	v_mfma_f32_16x16x32_bf16 v[58:61], v[146:149], v[184:187], 0
	v_mfma_f32_16x16x32_bf16 v[30:33], v[154:157], v[184:187], 0
	v_mfma_f32_16x16x32_bf16 v[54:57], v[146:149], v[192:195], 0
	v_mfma_f32_16x16x32_bf16 v[22:25], v[154:157], v[192:195], 0
	v_mfma_f32_16x16x32_bf16 v[50:53], v[146:149], v[200:203], 0
	v_mfma_f32_16x16x32_bf16 v[18:21], v[154:157], v[200:203], 0
	v_mfma_f32_16x16x32_bf16 v[66:69], v[150:153], v[166:169], v[66:69]
	v_mfma_f32_16x16x32_bf16 v[42:45], v[158:161], v[166:169], v[42:45]
	v_mfma_f32_16x16x32_bf16 v[58:61], v[150:153], v[188:191], v[58:61]
	v_mfma_f32_16x16x32_bf16 v[30:33], v[158:161], v[188:191], v[30:33]
	v_mfma_f32_16x16x32_bf16 v[54:57], v[150:153], v[196:199], v[54:57]
	v_mfma_f32_16x16x32_bf16 v[22:25], v[158:161], v[196:199], v[22:25]
	v_mfma_f32_16x16x32_bf16 v[50:53], v[150:153], v[210:213], v[50:53]
	v_mfma_f32_16x16x32_bf16 v[18:21], v[158:161], v[210:213], v[18:21]
	s_barrier
	ds_read_b128 v[162:165], v208 offset:16384
	s_add_i32 m0, s24, 0x10000
	ds_read_b128 v[166:169], v208 offset:17408
	global_load_lds_dwordx4 v178, s[16:17]
	s_add_i32 m0, s24, 0x12000
	s_add_u32 s46, s16, 0x80000
	s_addc_u32 s47, s17, 0
	ds_read_b128 v[184:187], v208 offset:18432
	global_load_lds_dwordx4 v176, s[16:17]
	s_add_i32 m0, s24, 0x14000
	ds_read_b128 v[188:191], v208 offset:19456
	global_load_lds_dwordx4 v178, s[46:47]
	s_add_i32 m0, s24, 0x16000
	ds_read_b128 v[192:195], v208 offset:20480
	global_load_lds_dwordx4 v176, s[46:47]
	s_mov_b32 m0, s25
	ds_read_b128 v[196:199], v208 offset:21504
	global_load_lds_dwordx4 v178, s[18:19]
	s_mov_b32 m0, s26
	ds_read_b128 v[200:203], v208 offset:22528
	global_load_lds_dwordx4 v176, s[18:19]
	ds_read_b128 v[210:213], v208 offset:23552
	s_waitcnt vmcnt(8) lgkmcnt(0)
	s_barrier
	v_mfma_f32_16x16x32_bf16 v[110:113], v[130:133], v[162:165], 0
	v_mfma_f32_16x16x32_bf16 v[78:81], v[138:141], v[162:165], 0
	v_mfma_f32_16x16x32_bf16 v[106:109], v[130:133], v[184:187], 0
	v_mfma_f32_16x16x32_bf16 v[74:77], v[138:141], v[184:187], 0
	v_mfma_f32_16x16x32_bf16 v[102:105], v[130:133], v[192:195], 0
	v_mfma_f32_16x16x32_bf16 v[70:73], v[138:141], v[192:195], 0
	v_mfma_f32_16x16x32_bf16 v[98:101], v[130:133], v[200:203], 0
	v_mfma_f32_16x16x32_bf16 v[62:65], v[138:141], v[200:203], 0
	v_mfma_f32_16x16x32_bf16 v[110:113], v[134:137], v[166:169], v[110:113]
	v_mfma_f32_16x16x32_bf16 v[78:81], v[142:145], v[166:169], v[78:81]
	v_mfma_f32_16x16x32_bf16 v[106:109], v[134:137], v[188:191], v[106:109]
	v_mfma_f32_16x16x32_bf16 v[74:77], v[142:145], v[188:191], v[74:77]
	v_mfma_f32_16x16x32_bf16 v[102:105], v[134:137], v[196:199], v[102:105]
	v_mfma_f32_16x16x32_bf16 v[70:73], v[142:145], v[196:199], v[70:73]
	v_mfma_f32_16x16x32_bf16 v[98:101], v[134:137], v[210:213], v[98:101]
	v_mfma_f32_16x16x32_bf16 v[62:65], v[142:145], v[210:213], v[62:65]
	v_mfma_f32_16x16x32_bf16 v[46:49], v[146:149], v[162:165], 0
	v_mfma_f32_16x16x32_bf16 v[12:15], v[154:157], v[162:165], 0
	v_mfma_f32_16x16x32_bf16 v[38:41], v[146:149], v[184:187], 0
	v_mfma_f32_16x16x32_bf16 v[8:11], v[154:157], v[184:187], 0
	v_mfma_f32_16x16x32_bf16 v[34:37], v[146:149], v[192:195], 0
	v_mfma_f32_16x16x32_bf16 v[4:7], v[154:157], v[192:195], 0
	v_mfma_f32_16x16x32_bf16 v[26:29], v[146:149], v[200:203], 0
	v_mfma_f32_16x16x32_bf16 v[0:3], v[154:157], v[200:203], 0
	v_mfma_f32_16x16x32_bf16 v[46:49], v[150:153], v[166:169], v[46:49]
	v_mfma_f32_16x16x32_bf16 v[12:15], v[158:161], v[166:169], v[12:15]
	v_mfma_f32_16x16x32_bf16 v[38:41], v[150:153], v[188:191], v[38:41]
	v_mfma_f32_16x16x32_bf16 v[8:11], v[158:161], v[188:191], v[8:11]
	v_mfma_f32_16x16x32_bf16 v[34:37], v[150:153], v[196:199], v[34:37]
	v_mfma_f32_16x16x32_bf16 v[4:7], v[158:161], v[196:199], v[4:7]
	v_mfma_f32_16x16x32_bf16 v[26:29], v[150:153], v[210:213], v[26:29]
	v_mfma_f32_16x16x32_bf16 v[0:3], v[158:161], v[210:213], v[0:3]
	s_barrier
	s_add_u32 s100, s18, 0x80000
	s_addc_u32 s101, s19, 0
	ds_read_b128 v[130:133], v172
	ds_read_b128 v[134:137], v172 offset:1024
	ds_read_b128 v[138:141], v172 offset:2048
	ds_read_b128 v[142:145], v172 offset:3072
	ds_read_b128 v[146:149], v173
	ds_read_b128 v[150:153], v173 offset:1024
	ds_read_b128 v[154:157], v173 offset:2048
	ds_read_b128 v[158:161], v173 offset:3072
	ds_read_b128 v[162:165], v208 offset:32768
	ds_read_b128 v[166:169], v208 offset:33792
	ds_read_b128 v[184:187], v208 offset:34816
	ds_read_b128 v[188:191], v208 offset:35840
	ds_read_b128 v[192:195], v208 offset:36864
	s_mov_b32 m0, s27
	ds_read_b128 v[196:199], v208 offset:37888
	global_load_lds_dwordx4 v178, s[100:101]
	s_mov_b32 m0, s28
	ds_read_b128 v[200:203], v208 offset:38912
	global_load_lds_dwordx4 v176, s[100:101]
	ds_read_b128 v[210:213], v208 offset:39936
	s_waitcnt vmcnt(8) lgkmcnt(0)
	s_barrier
	v_mfma_f32_16x16x32_bf16 v[126:129], v[130:133], v[162:165], v[126:129]
	v_mfma_f32_16x16x32_bf16 v[94:97], v[138:141], v[162:165], v[94:97]
	v_mfma_f32_16x16x32_bf16 v[122:125], v[130:133], v[184:187], v[122:125]
	v_mfma_f32_16x16x32_bf16 v[90:93], v[138:141], v[184:187], v[90:93]
	v_mfma_f32_16x16x32_bf16 v[118:121], v[130:133], v[192:195], v[118:121]
	v_mfma_f32_16x16x32_bf16 v[86:89], v[138:141], v[192:195], v[86:89]
	v_mfma_f32_16x16x32_bf16 v[114:117], v[130:133], v[200:203], v[114:117]
	v_mfma_f32_16x16x32_bf16 v[82:85], v[138:141], v[200:203], v[82:85]
	v_mfma_f32_16x16x32_bf16 v[126:129], v[134:137], v[166:169], v[126:129]
	v_mfma_f32_16x16x32_bf16 v[94:97], v[142:145], v[166:169], v[94:97]
	v_mfma_f32_16x16x32_bf16 v[122:125], v[134:137], v[188:191], v[122:125]
	v_mfma_f32_16x16x32_bf16 v[90:93], v[142:145], v[188:191], v[90:93]
	v_mfma_f32_16x16x32_bf16 v[118:121], v[134:137], v[196:199], v[118:121]
	v_mfma_f32_16x16x32_bf16 v[86:89], v[142:145], v[196:199], v[86:89]
	v_mfma_f32_16x16x32_bf16 v[114:117], v[134:137], v[210:213], v[114:117]
	v_mfma_f32_16x16x32_bf16 v[82:85], v[142:145], v[210:213], v[82:85]
	v_mfma_f32_16x16x32_bf16 v[66:69], v[146:149], v[162:165], v[66:69]
	v_mfma_f32_16x16x32_bf16 v[42:45], v[154:157], v[162:165], v[42:45]
	v_mfma_f32_16x16x32_bf16 v[58:61], v[146:149], v[184:187], v[58:61]
	v_mfma_f32_16x16x32_bf16 v[30:33], v[154:157], v[184:187], v[30:33]
	v_mfma_f32_16x16x32_bf16 v[54:57], v[146:149], v[192:195], v[54:57]
	v_mfma_f32_16x16x32_bf16 v[22:25], v[154:157], v[192:195], v[22:25]
	v_mfma_f32_16x16x32_bf16 v[50:53], v[146:149], v[200:203], v[50:53]
	v_mfma_f32_16x16x32_bf16 v[18:21], v[154:157], v[200:203], v[18:21]
	v_mfma_f32_16x16x32_bf16 v[66:69], v[150:153], v[166:169], v[66:69]
	v_mfma_f32_16x16x32_bf16 v[42:45], v[158:161], v[166:169], v[42:45]
	v_mfma_f32_16x16x32_bf16 v[58:61], v[150:153], v[188:191], v[58:61]
	v_mfma_f32_16x16x32_bf16 v[30:33], v[158:161], v[188:191], v[30:33]
	v_mfma_f32_16x16x32_bf16 v[54:57], v[150:153], v[196:199], v[54:57]
	v_mfma_f32_16x16x32_bf16 v[22:25], v[158:161], v[196:199], v[22:25]
	v_mfma_f32_16x16x32_bf16 v[50:53], v[150:153], v[210:213], v[50:53]
	v_mfma_f32_16x16x32_bf16 v[18:21], v[158:161], v[210:213], v[18:21]
	s_barrier
	ds_read_b128 v[162:165], v208 offset:49152
	s_add_i32 m0, s24, 0x17f80
	ds_read_b128 v[166:169], v208 offset:50176
	global_load_lds_dwordx4 v178, s[16:17] offset:128
	s_add_i32 m0, s24, 0x19f80
	ds_read_b128 v[184:187], v208 offset:51200
	global_load_lds_dwordx4 v176, s[16:17] offset:128
	s_add_i32 m0, s24, 0x1bf80
	ds_read_b128 v[188:191], v208 offset:52224
	global_load_lds_dwordx4 v178, s[46:47] offset:128
	s_add_i32 m0, s24, 0x1df80
	ds_read_b128 v[192:195], v208 offset:53248
	global_load_lds_dwordx4 v176, s[46:47] offset:128
	s_add_i32 m0, s35, 0xffffff80
	ds_read_b128 v[196:199], v208 offset:54272
	global_load_lds_dwordx4 v178, s[18:19] offset:128
	s_add_i32 m0, s36, 0xffffff80
	ds_read_b128 v[200:203], v208 offset:55296
	global_load_lds_dwordx4 v176, s[18:19] offset:128
	ds_read_b128 v[210:213], v208 offset:56320
	s_waitcnt vmcnt(8) lgkmcnt(0)
	s_barrier
	v_mfma_f32_16x16x32_bf16 v[110:113], v[130:133], v[162:165], v[110:113]
	v_mfma_f32_16x16x32_bf16 v[78:81], v[138:141], v[162:165], v[78:81]
	v_mfma_f32_16x16x32_bf16 v[106:109], v[130:133], v[184:187], v[106:109]
	v_mfma_f32_16x16x32_bf16 v[74:77], v[138:141], v[184:187], v[74:77]
	v_mfma_f32_16x16x32_bf16 v[102:105], v[130:133], v[192:195], v[102:105]
	v_mfma_f32_16x16x32_bf16 v[70:73], v[138:141], v[192:195], v[70:73]
	v_mfma_f32_16x16x32_bf16 v[98:101], v[130:133], v[200:203], v[98:101]
	v_mfma_f32_16x16x32_bf16 v[62:65], v[138:141], v[200:203], v[62:65]
	v_mfma_f32_16x16x32_bf16 v[110:113], v[134:137], v[166:169], v[110:113]
	v_mfma_f32_16x16x32_bf16 v[78:81], v[142:145], v[166:169], v[78:81]
	v_mfma_f32_16x16x32_bf16 v[106:109], v[134:137], v[188:191], v[106:109]
	v_mfma_f32_16x16x32_bf16 v[74:77], v[142:145], v[188:191], v[74:77]
	v_mfma_f32_16x16x32_bf16 v[102:105], v[134:137], v[196:199], v[102:105]
	v_mfma_f32_16x16x32_bf16 v[70:73], v[142:145], v[196:199], v[70:73]
	v_mfma_f32_16x16x32_bf16 v[98:101], v[134:137], v[210:213], v[98:101]
	v_mfma_f32_16x16x32_bf16 v[62:65], v[142:145], v[210:213], v[62:65]
	v_mfma_f32_16x16x32_bf16 v[46:49], v[146:149], v[162:165], v[46:49]
	v_mfma_f32_16x16x32_bf16 v[12:15], v[154:157], v[162:165], v[12:15]
	v_mfma_f32_16x16x32_bf16 v[38:41], v[146:149], v[184:187], v[38:41]
	v_mfma_f32_16x16x32_bf16 v[8:11], v[154:157], v[184:187], v[8:11]
	v_mfma_f32_16x16x32_bf16 v[34:37], v[146:149], v[192:195], v[34:37]
	v_mfma_f32_16x16x32_bf16 v[4:7], v[154:157], v[192:195], v[4:7]
	v_mfma_f32_16x16x32_bf16 v[26:29], v[146:149], v[200:203], v[26:29]
	v_mfma_f32_16x16x32_bf16 v[0:3], v[154:157], v[200:203], v[0:3]
	v_mfma_f32_16x16x32_bf16 v[46:49], v[150:153], v[166:169], v[46:49]
	v_mfma_f32_16x16x32_bf16 v[12:15], v[158:161], v[166:169], v[12:15]
	v_mfma_f32_16x16x32_bf16 v[38:41], v[150:153], v[188:191], v[38:41]
	v_mfma_f32_16x16x32_bf16 v[8:11], v[158:161], v[188:191], v[8:11]
	v_mfma_f32_16x16x32_bf16 v[34:37], v[150:153], v[196:199], v[34:37]
	v_mfma_f32_16x16x32_bf16 v[4:7], v[158:161], v[196:199], v[4:7]
	v_mfma_f32_16x16x32_bf16 v[26:29], v[150:153], v[210:213], v[26:29]
	v_mfma_f32_16x16x32_bf16 v[0:3], v[158:161], v[210:213], v[0:3]
	s_barrier
	s_add_i32 s44, s44, 2
	s_add_u32 s14, s14, 0x100
	s_addc_u32 s15, s15, 0
	s_add_u32 s42, s42, 0x100
	s_addc_u32 s43, s43, 0

.LBB0_551:
	s_ashr_i32 s19, s18, 31
	s_lshl_b64 s[20:21], s[18:19], 18
	s_add_u32 s17, s0, s20
	s_addc_u32 s19, s1, s21
	s_cmp_gt_i32 s16, 1
	s_cselect_b32 s20, 0x2000000, 0
	s_add_u32 s20, s17, s20
	s_addc_u32 s21, s19, 0
	s_and_b64 s[22:23], s[4:5], exec
	s_cselect_b32 s19, s21, s7
	s_cselect_b32 s42, s20, s6
	s_ashr_i32 s17, s16, 31
	s_lshl_b64 s[22:23], s[16:17], 18
	s_add_u32 s22, s28, s22
	s_addc_u32 s23, s29, s23
	s_and_b64 s[24:25], s[4:5], exec
	s_cselect_b32 s17, s23, s9
	s_cselect_b32 s43, s22, s8
	s_add_u32 s6, s6, 0x20080
	s_addc_u32 s7, s7, 0
	s_add_u32 s44, s8, 0x100
	s_addc_u32 s45, s9, 0
	s_mov_b32 s46, -2
	s_waitcnt vmcnt(0)
	v_add_u32_e32 v168, 0x10000, v184
	v_add_u32_e32 v169, 0x14000, v184
	v_add_u32_e32 v170, 0x18000, v184
	v_add_u32_e32 v171, 0x1c000, v184
	s_add_u32 s8, s6, 0xfffe0080
	s_addc_u32 s9, s7, -1
	s_cmp_eq_u32 s46, 4
	s_cselect_b32 s25, s19, s9
	s_cselect_b32 s24, s42, s8
	s_cselect_b32 s9, s17, s45
	s_cselect_b32 s8, s43, s44
	ds_read_b128 v[58:61], v168
	ds_read_b128 v[70:73], v168 offset:1024
	ds_read_b128 v[74:77], v168 offset:2048
	ds_read_b128 v[86:89], v168 offset:3072
	ds_read_b128 v[122:125], v169
	ds_read_b128 v[126:129], v169 offset:1024
	ds_read_b128 v[154:157], v169 offset:2048
	ds_read_b128 v[176:179], v169 offset:3072
	ds_read_b128 v[186:189], v185
	ds_read_b128 v[190:193], v185 offset:1024
	ds_read_b128 v[194:197], v185 offset:2048
	ds_read_b128 v[198:201], v185 offset:3072
	ds_read_b128 v[202:205], v185 offset:4096
	s_add_i32 m0, s31, 0xc000
	ds_read_b128 v[206:209], v185 offset:5120
	global_load_lds_dwordx4 v164, s[6:7]
	s_add_i32 m0, s31, 0xe000
	ds_read_b128 v[210:213], v185 offset:6144
	global_load_lds_dwordx4 v166, s[6:7]
	ds_read_b128 v[230:233], v185 offset:7168
	s_waitcnt vmcnt(8) lgkmcnt(0)
	s_barrier
	v_mfma_f32_16x16x32_bf16 v[150:153], v[58:61], v[186:189], 0
	v_mfma_f32_16x16x32_bf16 v[146:149], v[74:77], v[186:189], 0
	v_mfma_f32_16x16x32_bf16 v[142:145], v[58:61], v[194:197], 0
	v_mfma_f32_16x16x32_bf16 v[138:141], v[74:77], v[194:197], 0
	v_mfma_f32_16x16x32_bf16 v[134:137], v[58:61], v[202:205], 0
	v_mfma_f32_16x16x32_bf16 v[130:133], v[74:77], v[202:205], 0
	v_mfma_f32_16x16x32_bf16 v[118:121], v[58:61], v[210:213], 0
	v_mfma_f32_16x16x32_bf16 v[114:117], v[74:77], v[210:213], 0
	v_mfma_f32_16x16x32_bf16 v[150:153], v[70:73], v[190:193], v[150:153]
	v_mfma_f32_16x16x32_bf16 v[146:149], v[86:89], v[190:193], v[146:149]
	v_mfma_f32_16x16x32_bf16 v[142:145], v[70:73], v[198:201], v[142:145]
	v_mfma_f32_16x16x32_bf16 v[138:141], v[86:89], v[198:201], v[138:141]
	v_mfma_f32_16x16x32_bf16 v[134:137], v[70:73], v[206:209], v[134:137]
	v_mfma_f32_16x16x32_bf16 v[130:133], v[86:89], v[206:209], v[130:133]
	v_mfma_f32_16x16x32_bf16 v[118:121], v[70:73], v[230:233], v[118:121]
	v_mfma_f32_16x16x32_bf16 v[114:117], v[86:89], v[230:233], v[114:117]
	v_mfma_f32_16x16x32_bf16 v[66:69], v[122:125], v[186:189], 0
	v_mfma_f32_16x16x32_bf16 v[62:65], v[154:157], v[186:189], 0
	v_mfma_f32_16x16x32_bf16 v[54:57], v[122:125], v[194:197], 0
	v_mfma_f32_16x16x32_bf16 v[50:53], v[154:157], v[194:197], 0
	v_mfma_f32_16x16x32_bf16 v[46:49], v[122:125], v[202:205], 0
	v_mfma_f32_16x16x32_bf16 v[42:45], v[154:157], v[202:205], 0
	v_mfma_f32_16x16x32_bf16 v[38:41], v[122:125], v[210:213], 0
	v_mfma_f32_16x16x32_bf16 v[34:37], v[154:157], v[210:213], 0
	v_mfma_f32_16x16x32_bf16 v[66:69], v[126:129], v[190:193], v[66:69]
	v_mfma_f32_16x16x32_bf16 v[62:65], v[176:179], v[190:193], v[62:65]
	v_mfma_f32_16x16x32_bf16 v[54:57], v[126:129], v[198:201], v[54:57]
	v_mfma_f32_16x16x32_bf16 v[50:53], v[176:179], v[198:201], v[50:53]
	v_mfma_f32_16x16x32_bf16 v[46:49], v[126:129], v[206:209], v[46:49]
	v_mfma_f32_16x16x32_bf16 v[42:45], v[176:179], v[206:209], v[42:45]
	v_mfma_f32_16x16x32_bf16 v[38:41], v[126:129], v[230:233], v[38:41]
	v_mfma_f32_16x16x32_bf16 v[34:37], v[176:179], v[230:233], v[34:37]
	s_barrier
	ds_read_b128 v[186:189], v185 offset:16384
	s_add_i32 m0, s30, 0x10000
	ds_read_b128 v[190:193], v185 offset:17408
	global_load_lds_dwordx4 v16, s[8:9]
	s_add_i32 m0, s30, 0x12000
	s_add_u32 s48, s8, 0x20000
	s_addc_u32 s49, s9, 0
	ds_read_b128 v[194:197], v185 offset:18432
	global_load_lds_dwordx4 v158, s[8:9]
	s_add_i32 m0, s30, 0x14000
	ds_read_b128 v[198:201], v185 offset:19456
	global_load_lds_dwordx4 v16, s[48:49]
	s_add_i32 m0, s30, 0x16000
	ds_read_b128 v[202:205], v185 offset:20480
	global_load_lds_dwordx4 v158, s[48:49]
	s_mov_b32 m0, s31
	ds_read_b128 v[206:209], v185 offset:21504
	global_load_lds_dwordx4 v162, s[24:25]
	s_mov_b32 m0, s34
	ds_read_b128 v[210:213], v185 offset:22528
	global_load_lds_dwordx4 v160, s[24:25]
	ds_read_b128 v[230:233], v185 offset:23552
	s_waitcnt vmcnt(8) lgkmcnt(0)
	s_barrier
	v_mfma_f32_16x16x32_bf16 v[110:113], v[58:61], v[186:189], 0
	v_mfma_f32_16x16x32_bf16 v[106:109], v[74:77], v[186:189], 0
	v_mfma_f32_16x16x32_bf16 v[102:105], v[58:61], v[194:197], 0
	v_mfma_f32_16x16x32_bf16 v[98:101], v[74:77], v[194:197], 0
	v_mfma_f32_16x16x32_bf16 v[94:97], v[58:61], v[202:205], 0
	v_mfma_f32_16x16x32_bf16 v[90:93], v[74:77], v[202:205], 0
	v_mfma_f32_16x16x32_bf16 v[58:61], v[58:61], v[210:213], 0
	v_mfma_f32_16x16x32_bf16 v[110:113], v[70:73], v[190:193], v[110:113]
	v_mfma_f32_16x16x32_bf16 v[106:109], v[86:89], v[190:193], v[106:109]
	v_mfma_f32_16x16x32_bf16 v[102:105], v[70:73], v[198:201], v[102:105]
	v_mfma_f32_16x16x32_bf16 v[98:101], v[86:89], v[198:201], v[98:101]
	v_mfma_f32_16x16x32_bf16 v[94:97], v[70:73], v[206:209], v[94:97]
	v_mfma_f32_16x16x32_bf16 v[90:93], v[86:89], v[206:209], v[90:93]
	v_mfma_f32_16x16x32_bf16 v[58:61], v[70:73], v[230:233], v[58:61]
	v_mfma_f32_16x16x32_bf16 v[70:73], v[74:77], v[210:213], 0
	v_mfma_f32_16x16x32_bf16 v[70:73], v[86:89], v[230:233], v[70:73]
	v_mfma_f32_16x16x32_bf16 v[30:33], v[122:125], v[186:189], 0
	v_mfma_f32_16x16x32_bf16 v[26:29], v[154:157], v[186:189], 0
	v_mfma_f32_16x16x32_bf16 v[22:25], v[122:125], v[194:197], 0
	v_mfma_f32_16x16x32_bf16 v[18:21], v[154:157], v[194:197], 0
	v_mfma_f32_16x16x32_bf16 v[12:15], v[122:125], v[202:205], 0
	v_mfma_f32_16x16x32_bf16 v[8:11], v[154:157], v[202:205], 0
	v_mfma_f32_16x16x32_bf16 v[4:7], v[122:125], v[210:213], 0
	v_mfma_f32_16x16x32_bf16 v[0:3], v[154:157], v[210:213], 0
	v_mfma_f32_16x16x32_bf16 v[30:33], v[126:129], v[190:193], v[30:33]
	v_mfma_f32_16x16x32_bf16 v[26:29], v[176:179], v[190:193], v[26:29]
	v_mfma_f32_16x16x32_bf16 v[22:25], v[126:129], v[198:201], v[22:25]
	v_mfma_f32_16x16x32_bf16 v[18:21], v[176:179], v[198:201], v[18:21]
	v_mfma_f32_16x16x32_bf16 v[12:15], v[126:129], v[206:209], v[12:15]
	v_mfma_f32_16x16x32_bf16 v[8:11], v[176:179], v[206:209], v[8:11]
	v_mfma_f32_16x16x32_bf16 v[4:7], v[126:129], v[230:233], v[4:7]
	v_mfma_f32_16x16x32_bf16 v[0:3], v[176:179], v[230:233], v[0:3]
	s_barrier
	s_add_u32 s100, s24, 0x20000
	s_addc_u32 s101, s25, 0
	ds_read_b128 v[74:77], v170
	ds_read_b128 v[78:81], v170 offset:1024
	ds_read_b128 v[86:89], v170 offset:2048
	ds_read_b128 v[122:125], v170 offset:3072
	ds_read_b128 v[126:129], v171
	ds_read_b128 v[154:157], v171 offset:1024
	ds_read_b128 v[176:179], v171 offset:2048
	ds_read_b128 v[186:189], v171 offset:3072
	ds_read_b128 v[82:85], v185 offset:32768
	ds_read_b128 v[190:193], v185 offset:33792
	ds_read_b128 v[194:197], v185 offset:34816
	ds_read_b128 v[198:201], v185 offset:35840
	ds_read_b128 v[202:205], v185 offset:36864
	s_mov_b32 m0, s35
	ds_read_b128 v[206:209], v185 offset:37888
	global_load_lds_dwordx4 v162, s[100:101]
	s_mov_b32 m0, s36
	ds_read_b128 v[210:213], v185 offset:38912
	global_load_lds_dwordx4 v160, s[100:101]
	ds_read_b128 v[230:233], v185 offset:39936
	s_waitcnt vmcnt(8) lgkmcnt(0)
	s_barrier
	v_mfma_f32_16x16x32_bf16 v[150:153], v[74:77], v[82:85], v[150:153]
	v_mfma_f32_16x16x32_bf16 v[146:149], v[86:89], v[82:85], v[146:149]
	v_mfma_f32_16x16x32_bf16 v[142:145], v[74:77], v[194:197], v[142:145]
	v_mfma_f32_16x16x32_bf16 v[138:141], v[86:89], v[194:197], v[138:141]
	v_mfma_f32_16x16x32_bf16 v[134:137], v[74:77], v[202:205], v[134:137]
	v_mfma_f32_16x16x32_bf16 v[130:133], v[86:89], v[202:205], v[130:133]
	v_mfma_f32_16x16x32_bf16 v[118:121], v[74:77], v[210:213], v[118:121]
	v_mfma_f32_16x16x32_bf16 v[114:117], v[86:89], v[210:213], v[114:117]
	v_mfma_f32_16x16x32_bf16 v[150:153], v[78:81], v[190:193], v[150:153]
	v_mfma_f32_16x16x32_bf16 v[146:149], v[122:125], v[190:193], v[146:149]
	v_mfma_f32_16x16x32_bf16 v[142:145], v[78:81], v[198:201], v[142:145]
	v_mfma_f32_16x16x32_bf16 v[138:141], v[122:125], v[198:201], v[138:141]
	v_mfma_f32_16x16x32_bf16 v[134:137], v[78:81], v[206:209], v[134:137]
	v_mfma_f32_16x16x32_bf16 v[130:133], v[122:125], v[206:209], v[130:133]
	v_mfma_f32_16x16x32_bf16 v[118:121], v[78:81], v[230:233], v[118:121]
	v_mfma_f32_16x16x32_bf16 v[114:117], v[122:125], v[230:233], v[114:117]
	v_mfma_f32_16x16x32_bf16 v[66:69], v[126:129], v[82:85], v[66:69]
	v_mfma_f32_16x16x32_bf16 v[62:65], v[176:179], v[82:85], v[62:65]
	v_mfma_f32_16x16x32_bf16 v[54:57], v[126:129], v[194:197], v[54:57]
	v_mfma_f32_16x16x32_bf16 v[50:53], v[176:179], v[194:197], v[50:53]
	v_mfma_f32_16x16x32_bf16 v[46:49], v[126:129], v[202:205], v[46:49]
	v_mfma_f32_16x16x32_bf16 v[42:45], v[176:179], v[202:205], v[42:45]
	v_mfma_f32_16x16x32_bf16 v[38:41], v[126:129], v[210:213], v[38:41]
	v_mfma_f32_16x16x32_bf16 v[34:37], v[176:179], v[210:213], v[34:37]
	v_mfma_f32_16x16x32_bf16 v[66:69], v[154:157], v[190:193], v[66:69]
	v_mfma_f32_16x16x32_bf16 v[62:65], v[186:189], v[190:193], v[62:65]
	v_mfma_f32_16x16x32_bf16 v[54:57], v[154:157], v[198:201], v[54:57]
	v_mfma_f32_16x16x32_bf16 v[50:53], v[186:189], v[198:201], v[50:53]
	v_mfma_f32_16x16x32_bf16 v[46:49], v[154:157], v[206:209], v[46:49]
	v_mfma_f32_16x16x32_bf16 v[42:45], v[186:189], v[206:209], v[42:45]
	v_mfma_f32_16x16x32_bf16 v[38:41], v[154:157], v[230:233], v[38:41]
	v_mfma_f32_16x16x32_bf16 v[34:37], v[186:189], v[230:233], v[34:37]
	s_barrier
	ds_read_b128 v[190:193], v185 offset:49152
	s_add_i32 m0, s30, 0x17f80
	ds_read_b128 v[194:197], v185 offset:50176
	global_load_lds_dwordx4 v16, s[8:9] offset:128
	s_add_i32 m0, s30, 0x19f80
	ds_read_b128 v[198:201], v185 offset:51200
	global_load_lds_dwordx4 v158, s[8:9] offset:128
	s_add_i32 m0, s30, 0x1bf80
	ds_read_b128 v[202:205], v185 offset:52224
	global_load_lds_dwordx4 v16, s[48:49] offset:128
	s_add_i32 m0, s30, 0x1df80
	ds_read_b128 v[206:209], v185 offset:53248
	global_load_lds_dwordx4 v158, s[48:49] offset:128
	s_add_i32 m0, s38, 0xffffff80
	ds_read_b128 v[210:213], v185 offset:54272
	global_load_lds_dwordx4 v162, s[24:25] offset:128
	s_add_i32 m0, s39, 0xffffff80
	ds_read_b128 v[230:233], v185 offset:55296
	global_load_lds_dwordx4 v160, s[24:25] offset:128
	ds_read_b128 v[234:237], v185 offset:56320
	s_waitcnt vmcnt(8) lgkmcnt(0)
	s_barrier
	v_mfma_f32_16x16x32_bf16 v[82:85], v[74:77], v[190:193], v[110:113]
	v_mfma_f32_16x16x32_bf16 v[110:113], v[78:81], v[194:197], v[82:85]
	v_mfma_f32_16x16x32_bf16 v[82:85], v[86:89], v[190:193], v[106:109]
	v_mfma_f32_16x16x32_bf16 v[106:109], v[122:125], v[194:197], v[82:85]
	v_mfma_f32_16x16x32_bf16 v[82:85], v[74:77], v[198:201], v[102:105]
	v_mfma_f32_16x16x32_bf16 v[102:105], v[78:81], v[202:205], v[82:85]
	v_mfma_f32_16x16x32_bf16 v[82:85], v[86:89], v[198:201], v[98:101]
	v_mfma_f32_16x16x32_bf16 v[98:101], v[122:125], v[202:205], v[82:85]
	v_mfma_f32_16x16x32_bf16 v[82:85], v[74:77], v[206:209], v[94:97]
	v_mfma_f32_16x16x32_bf16 v[94:97], v[78:81], v[210:213], v[82:85]
	v_mfma_f32_16x16x32_bf16 v[82:85], v[86:89], v[206:209], v[90:93]
	v_mfma_f32_16x16x32_bf16 v[58:61], v[74:77], v[230:233], v[58:61]
	v_mfma_f32_16x16x32_bf16 v[90:93], v[122:125], v[210:213], v[82:85]
	v_mfma_f32_16x16x32_bf16 v[82:85], v[78:81], v[234:237], v[58:61]
	v_mfma_f32_16x16x32_bf16 v[58:61], v[86:89], v[230:233], v[70:73]
	v_mfma_f32_16x16x32_bf16 v[78:81], v[122:125], v[234:237], v[58:61]
	v_mfma_f32_16x16x32_bf16 v[30:33], v[126:129], v[190:193], v[30:33]
	v_mfma_f32_16x16x32_bf16 v[26:29], v[176:179], v[190:193], v[26:29]
	v_mfma_f32_16x16x32_bf16 v[22:25], v[126:129], v[198:201], v[22:25]
	v_mfma_f32_16x16x32_bf16 v[18:21], v[176:179], v[198:201], v[18:21]
	v_mfma_f32_16x16x32_bf16 v[12:15], v[126:129], v[206:209], v[12:15]
	v_mfma_f32_16x16x32_bf16 v[8:11], v[176:179], v[206:209], v[8:11]
	v_mfma_f32_16x16x32_bf16 v[4:7], v[126:129], v[230:233], v[4:7]
	v_mfma_f32_16x16x32_bf16 v[0:3], v[176:179], v[230:233], v[0:3]
	v_mfma_f32_16x16x32_bf16 v[30:33], v[154:157], v[194:197], v[30:33]
	v_mfma_f32_16x16x32_bf16 v[26:29], v[186:189], v[194:197], v[26:29]
	v_mfma_f32_16x16x32_bf16 v[22:25], v[154:157], v[202:205], v[22:25]
	v_mfma_f32_16x16x32_bf16 v[18:21], v[186:189], v[202:205], v[18:21]
	v_mfma_f32_16x16x32_bf16 v[12:15], v[154:157], v[210:213], v[12:15]
	v_mfma_f32_16x16x32_bf16 v[8:11], v[186:189], v[210:213], v[8:11]
	v_mfma_f32_16x16x32_bf16 v[4:7], v[154:157], v[234:237], v[4:7]
	v_mfma_f32_16x16x32_bf16 v[0:3], v[186:189], v[234:237], v[0:3]
	s_barrier
	s_add_i32 s46, s46, 2
	s_add_u32 s6, s6, 0x100
	s_addc_u32 s7, s7, 0
	s_add_u32 s44, s44, 0x100
	s_addc_u32 s45, s45, 0

.LBB0_1017:
	s_ashr_i32 s19, s18, 31
	s_lshl_b64 s[20:21], s[18:19], 20
	s_add_u32 s20, s34, s20
	s_addc_u32 s21, s35, s21
	s_and_b64 s[22:23], s[4:5], exec
	s_cselect_b32 s19, s21, s25
	s_cselect_b32 s31, s20, s24
	s_ashr_i32 s17, s16, 31
	s_lshl_b64 s[22:23], s[16:17], 20
	s_add_u32 s22, s36, s22
	s_addc_u32 s23, s37, s23
	s_and_b64 s[28:29], s[4:5], exec
	s_cselect_b32 s17, s23, s27
	s_cselect_b32 s55, s22, s26
	s_add_u32 s24, s24, 0x80080
	s_addc_u32 s25, s25, 0
	s_add_u32 s60, s26, 0x100
	s_addc_u32 s61, s27, 0
	s_mov_b32 s62, -2
	v_add_u32_e32 v168, 0x10000, v166
	v_add_u32_e32 v169, 0x14000, v166
	v_add_u32_e32 v170, 0x18000, v166
	v_add_u32_e32 v171, 0x1c000, v166
	s_add_u32 s26, s24, 0xfff80080
	s_addc_u32 s27, s25, -1
	s_cmp_eq_u32 s62, 28
	s_cselect_b32 s29, s19, s27
	s_cselect_b32 s28, s31, s26
	s_cselect_b32 s27, s17, s61
	s_cselect_b32 s26, s55, s60
	ds_read_b128 v[144:147], v168
	ds_read_b128 v[148:151], v168 offset:1024
	ds_read_b128 v[152:155], v168 offset:2048
	ds_read_b128 v[156:159], v168 offset:3072
	ds_read_b128 v[160:163], v169
	ds_read_b128 v[176:179], v169 offset:1024
	ds_read_b128 v[180:183], v169 offset:2048
	ds_read_b128 v[184:187], v169 offset:3072
	ds_read_b128 v[188:191], v167
	ds_read_b128 v[192:195], v167 offset:1024
	ds_read_b128 v[196:199], v167 offset:2048
	ds_read_b128 v[200:203], v167 offset:3072
	ds_read_b128 v[204:207], v167 offset:4096
	s_add_i32 m0, s39, 0xc000
	ds_read_b128 v[208:211], v167 offset:5120
	global_load_lds_dwordx4 v140, s[24:25]
	s_add_i32 m0, s39, 0xe000
	ds_read_b128 v[212:215], v167 offset:6144
	global_load_lds_dwordx4 v142, s[24:25]
	ds_read_b128 v[230:233], v167 offset:7168
	s_waitcnt vmcnt(8) lgkmcnt(0)
	s_barrier
	v_mfma_f32_16x16x32_bf16 v[66:69], v[144:147], v[188:191], 0
	v_mfma_f32_16x16x32_bf16 v[62:65], v[152:155], v[188:191], 0
	v_mfma_f32_16x16x32_bf16 v[58:61], v[144:147], v[196:199], 0
	v_mfma_f32_16x16x32_bf16 v[54:57], v[152:155], v[196:199], 0
	v_mfma_f32_16x16x32_bf16 v[46:49], v[144:147], v[204:207], 0
	v_mfma_f32_16x16x32_bf16 v[42:45], v[152:155], v[204:207], 0
	v_mfma_f32_16x16x32_bf16 v[38:41], v[144:147], v[212:215], 0
	v_mfma_f32_16x16x32_bf16 v[34:37], v[152:155], v[212:215], 0
	v_mfma_f32_16x16x32_bf16 v[66:69], v[148:151], v[192:195], v[66:69]
	v_mfma_f32_16x16x32_bf16 v[62:65], v[156:159], v[192:195], v[62:65]
	v_mfma_f32_16x16x32_bf16 v[58:61], v[148:151], v[200:203], v[58:61]
	v_mfma_f32_16x16x32_bf16 v[54:57], v[156:159], v[200:203], v[54:57]
	v_mfma_f32_16x16x32_bf16 v[46:49], v[148:151], v[208:211], v[46:49]
	v_mfma_f32_16x16x32_bf16 v[42:45], v[156:159], v[208:211], v[42:45]
	v_mfma_f32_16x16x32_bf16 v[38:41], v[148:151], v[230:233], v[38:41]
	v_mfma_f32_16x16x32_bf16 v[34:37], v[156:159], v[230:233], v[34:37]
	v_mfma_f32_16x16x32_bf16 v[126:129], v[160:163], v[188:191], 0
	v_mfma_f32_16x16x32_bf16 v[122:125], v[180:183], v[188:191], 0
	v_mfma_f32_16x16x32_bf16 v[118:121], v[160:163], v[196:199], 0
	v_mfma_f32_16x16x32_bf16 v[114:117], v[180:183], v[196:199], 0
	v_mfma_f32_16x16x32_bf16 v[110:113], v[160:163], v[204:207], 0
	v_mfma_f32_16x16x32_bf16 v[106:109], v[180:183], v[204:207], 0
	v_mfma_f32_16x16x32_bf16 v[102:105], v[160:163], v[212:215], 0
	v_mfma_f32_16x16x32_bf16 v[98:101], v[180:183], v[212:215], 0
	v_mfma_f32_16x16x32_bf16 v[126:129], v[176:179], v[192:195], v[126:129]
	v_mfma_f32_16x16x32_bf16 v[122:125], v[184:187], v[192:195], v[122:125]
	v_mfma_f32_16x16x32_bf16 v[118:121], v[176:179], v[200:203], v[118:121]
	v_mfma_f32_16x16x32_bf16 v[114:117], v[184:187], v[200:203], v[114:117]
	v_mfma_f32_16x16x32_bf16 v[110:113], v[176:179], v[208:211], v[110:113]
	v_mfma_f32_16x16x32_bf16 v[106:109], v[184:187], v[208:211], v[106:109]
	v_mfma_f32_16x16x32_bf16 v[102:105], v[176:179], v[230:233], v[102:105]
	v_mfma_f32_16x16x32_bf16 v[98:101], v[184:187], v[230:233], v[98:101]
	s_barrier
	ds_read_b128 v[188:191], v167 offset:16384
	s_add_i32 m0, s38, 0x10000
	ds_read_b128 v[192:195], v167 offset:17408
	global_load_lds_dwordx4 v132, s[26:27]
	s_add_i32 m0, s38, 0x12000
	s_add_u32 s64, s26, 0x80000
	s_addc_u32 s65, s27, 0
	ds_read_b128 v[196:199], v167 offset:18432
	global_load_lds_dwordx4 v136, s[26:27]
	s_add_i32 m0, s38, 0x14000
	ds_read_b128 v[200:203], v167 offset:19456
	global_load_lds_dwordx4 v132, s[64:65]
	s_add_i32 m0, s38, 0x16000
	ds_read_b128 v[204:207], v167 offset:20480
	global_load_lds_dwordx4 v136, s[64:65]
	s_mov_b32 m0, s39
	ds_read_b128 v[208:211], v167 offset:21504
	global_load_lds_dwordx4 v130, s[28:29]
	s_mov_b32 m0, s40
	ds_read_b128 v[212:215], v167 offset:22528
	global_load_lds_dwordx4 v134, s[28:29]
	ds_read_b128 v[230:233], v167 offset:23552
	s_waitcnt vmcnt(8) lgkmcnt(0)
	s_barrier
	v_mfma_f32_16x16x32_bf16 v[30:33], v[144:147], v[188:191], 0
	v_mfma_f32_16x16x32_bf16 v[26:29], v[152:155], v[188:191], 0
	v_mfma_f32_16x16x32_bf16 v[22:25], v[144:147], v[196:199], 0
	v_mfma_f32_16x16x32_bf16 v[18:21], v[152:155], v[196:199], 0
	v_mfma_f32_16x16x32_bf16 v[12:15], v[144:147], v[204:207], 0
	v_mfma_f32_16x16x32_bf16 v[8:11], v[152:155], v[204:207], 0
	v_mfma_f32_16x16x32_bf16 v[4:7], v[144:147], v[212:215], 0
	v_mfma_f32_16x16x32_bf16 v[0:3], v[152:155], v[212:215], 0
	v_mfma_f32_16x16x32_bf16 v[30:33], v[148:151], v[192:195], v[30:33]
	v_mfma_f32_16x16x32_bf16 v[26:29], v[156:159], v[192:195], v[26:29]
	v_mfma_f32_16x16x32_bf16 v[22:25], v[148:151], v[200:203], v[22:25]
	v_mfma_f32_16x16x32_bf16 v[18:21], v[156:159], v[200:203], v[18:21]
	v_mfma_f32_16x16x32_bf16 v[12:15], v[148:151], v[208:211], v[12:15]
	v_mfma_f32_16x16x32_bf16 v[8:11], v[156:159], v[208:211], v[8:11]
	v_mfma_f32_16x16x32_bf16 v[4:7], v[148:151], v[230:233], v[4:7]
	v_mfma_f32_16x16x32_bf16 v[0:3], v[156:159], v[230:233], v[0:3]
	v_mfma_f32_16x16x32_bf16 v[94:97], v[160:163], v[188:191], 0
	v_mfma_f32_16x16x32_bf16 v[90:93], v[180:183], v[188:191], 0
	v_mfma_f32_16x16x32_bf16 v[86:89], v[160:163], v[196:199], 0
	v_mfma_f32_16x16x32_bf16 v[82:85], v[180:183], v[196:199], 0
	v_mfma_f32_16x16x32_bf16 v[78:81], v[160:163], v[204:207], 0
	v_mfma_f32_16x16x32_bf16 v[74:77], v[180:183], v[204:207], 0
	v_mfma_f32_16x16x32_bf16 v[70:73], v[160:163], v[212:215], 0
	v_mfma_f32_16x16x32_bf16 v[50:53], v[180:183], v[212:215], 0
	v_mfma_f32_16x16x32_bf16 v[94:97], v[176:179], v[192:195], v[94:97]
	v_mfma_f32_16x16x32_bf16 v[90:93], v[184:187], v[192:195], v[90:93]
	v_mfma_f32_16x16x32_bf16 v[86:89], v[176:179], v[200:203], v[86:89]
	v_mfma_f32_16x16x32_bf16 v[82:85], v[184:187], v[200:203], v[82:85]
	v_mfma_f32_16x16x32_bf16 v[78:81], v[176:179], v[208:211], v[78:81]
	v_mfma_f32_16x16x32_bf16 v[74:77], v[184:187], v[208:211], v[74:77]
	v_mfma_f32_16x16x32_bf16 v[70:73], v[176:179], v[230:233], v[70:73]
	v_mfma_f32_16x16x32_bf16 v[50:53], v[184:187], v[230:233], v[50:53]
	s_barrier
	s_add_u32 s100, s28, 0x80000
	s_addc_u32 s101, s29, 0
	ds_read_b128 v[144:147], v170
	ds_read_b128 v[148:151], v170 offset:1024
	ds_read_b128 v[152:155], v170 offset:2048
	ds_read_b128 v[156:159], v170 offset:3072
	ds_read_b128 v[160:163], v171
	ds_read_b128 v[176:179], v171 offset:1024
	ds_read_b128 v[180:183], v171 offset:2048
	ds_read_b128 v[184:187], v171 offset:3072
	ds_read_b128 v[188:191], v167 offset:32768
	ds_read_b128 v[192:195], v167 offset:33792
	ds_read_b128 v[196:199], v167 offset:34816
	ds_read_b128 v[200:203], v167 offset:35840
	ds_read_b128 v[204:207], v167 offset:36864
	s_mov_b32 m0, s41
	ds_read_b128 v[208:211], v167 offset:37888
	global_load_lds_dwordx4 v130, s[100:101]
	s_mov_b32 m0, s42
	ds_read_b128 v[212:215], v167 offset:38912
	global_load_lds_dwordx4 v134, s[100:101]
	ds_read_b128 v[230:233], v167 offset:39936
	s_waitcnt vmcnt(8) lgkmcnt(0)
	s_barrier
	v_mfma_f32_16x16x32_bf16 v[66:69], v[144:147], v[188:191], v[66:69]
	v_mfma_f32_16x16x32_bf16 v[62:65], v[152:155], v[188:191], v[62:65]
	v_mfma_f32_16x16x32_bf16 v[58:61], v[144:147], v[196:199], v[58:61]
	v_mfma_f32_16x16x32_bf16 v[54:57], v[152:155], v[196:199], v[54:57]
	v_mfma_f32_16x16x32_bf16 v[46:49], v[144:147], v[204:207], v[46:49]
	v_mfma_f32_16x16x32_bf16 v[42:45], v[152:155], v[204:207], v[42:45]
	v_mfma_f32_16x16x32_bf16 v[38:41], v[144:147], v[212:215], v[38:41]
	v_mfma_f32_16x16x32_bf16 v[34:37], v[152:155], v[212:215], v[34:37]
	v_mfma_f32_16x16x32_bf16 v[66:69], v[148:151], v[192:195], v[66:69]
	v_mfma_f32_16x16x32_bf16 v[62:65], v[156:159], v[192:195], v[62:65]
	v_mfma_f32_16x16x32_bf16 v[58:61], v[148:151], v[200:203], v[58:61]
	v_mfma_f32_16x16x32_bf16 v[54:57], v[156:159], v[200:203], v[54:57]
	v_mfma_f32_16x16x32_bf16 v[46:49], v[148:151], v[208:211], v[46:49]
	v_mfma_f32_16x16x32_bf16 v[42:45], v[156:159], v[208:211], v[42:45]
	v_mfma_f32_16x16x32_bf16 v[38:41], v[148:151], v[230:233], v[38:41]
	v_mfma_f32_16x16x32_bf16 v[34:37], v[156:159], v[230:233], v[34:37]
	v_mfma_f32_16x16x32_bf16 v[126:129], v[160:163], v[188:191], v[126:129]
	v_mfma_f32_16x16x32_bf16 v[122:125], v[180:183], v[188:191], v[122:125]
	v_mfma_f32_16x16x32_bf16 v[118:121], v[160:163], v[196:199], v[118:121]
	v_mfma_f32_16x16x32_bf16 v[114:117], v[180:183], v[196:199], v[114:117]
	v_mfma_f32_16x16x32_bf16 v[110:113], v[160:163], v[204:207], v[110:113]
	v_mfma_f32_16x16x32_bf16 v[106:109], v[180:183], v[204:207], v[106:109]
	v_mfma_f32_16x16x32_bf16 v[102:105], v[160:163], v[212:215], v[102:105]
	v_mfma_f32_16x16x32_bf16 v[98:101], v[180:183], v[212:215], v[98:101]
	v_mfma_f32_16x16x32_bf16 v[126:129], v[176:179], v[192:195], v[126:129]
	v_mfma_f32_16x16x32_bf16 v[122:125], v[184:187], v[192:195], v[122:125]
	v_mfma_f32_16x16x32_bf16 v[118:121], v[176:179], v[200:203], v[118:121]
	v_mfma_f32_16x16x32_bf16 v[114:117], v[184:187], v[200:203], v[114:117]
	v_mfma_f32_16x16x32_bf16 v[110:113], v[176:179], v[208:211], v[110:113]
	v_mfma_f32_16x16x32_bf16 v[106:109], v[184:187], v[208:211], v[106:109]
	v_mfma_f32_16x16x32_bf16 v[102:105], v[176:179], v[230:233], v[102:105]
	v_mfma_f32_16x16x32_bf16 v[98:101], v[184:187], v[230:233], v[98:101]
	s_barrier
	ds_read_b128 v[188:191], v167 offset:49152
	s_add_i32 m0, s38, 0x17f80
	ds_read_b128 v[192:195], v167 offset:50176
	global_load_lds_dwordx4 v132, s[26:27] offset:128
	s_add_i32 m0, s38, 0x19f80
	ds_read_b128 v[196:199], v167 offset:51200
	global_load_lds_dwordx4 v136, s[26:27] offset:128
	s_add_i32 m0, s38, 0x1bf80
	ds_read_b128 v[200:203], v167 offset:52224
	global_load_lds_dwordx4 v132, s[64:65] offset:128
	s_add_i32 m0, s38, 0x1df80
	ds_read_b128 v[204:207], v167 offset:53248
	global_load_lds_dwordx4 v136, s[64:65] offset:128
	s_add_i32 m0, s46, 0xffffff80
	ds_read_b128 v[208:211], v167 offset:54272
	global_load_lds_dwordx4 v130, s[28:29] offset:128
	s_add_i32 m0, s47, 0xffffff80
	ds_read_b128 v[212:215], v167 offset:55296
	global_load_lds_dwordx4 v134, s[28:29] offset:128
	ds_read_b128 v[230:233], v167 offset:56320
	s_waitcnt vmcnt(8) lgkmcnt(0)
	s_barrier
	v_mfma_f32_16x16x32_bf16 v[30:33], v[144:147], v[188:191], v[30:33]
	v_mfma_f32_16x16x32_bf16 v[26:29], v[152:155], v[188:191], v[26:29]
	v_mfma_f32_16x16x32_bf16 v[22:25], v[144:147], v[196:199], v[22:25]
	v_mfma_f32_16x16x32_bf16 v[18:21], v[152:155], v[196:199], v[18:21]
	v_mfma_f32_16x16x32_bf16 v[12:15], v[144:147], v[204:207], v[12:15]
	v_mfma_f32_16x16x32_bf16 v[8:11], v[152:155], v[204:207], v[8:11]
	v_mfma_f32_16x16x32_bf16 v[4:7], v[144:147], v[212:215], v[4:7]
	v_mfma_f32_16x16x32_bf16 v[0:3], v[152:155], v[212:215], v[0:3]
	v_mfma_f32_16x16x32_bf16 v[30:33], v[148:151], v[192:195], v[30:33]
	v_mfma_f32_16x16x32_bf16 v[26:29], v[156:159], v[192:195], v[26:29]
	v_mfma_f32_16x16x32_bf16 v[22:25], v[148:151], v[200:203], v[22:25]
	v_mfma_f32_16x16x32_bf16 v[18:21], v[156:159], v[200:203], v[18:21]
	v_mfma_f32_16x16x32_bf16 v[12:15], v[148:151], v[208:211], v[12:15]
	v_mfma_f32_16x16x32_bf16 v[8:11], v[156:159], v[208:211], v[8:11]
	v_mfma_f32_16x16x32_bf16 v[4:7], v[148:151], v[230:233], v[4:7]
	v_mfma_f32_16x16x32_bf16 v[0:3], v[156:159], v[230:233], v[0:3]
	v_mfma_f32_16x16x32_bf16 v[94:97], v[160:163], v[188:191], v[94:97]
	v_mfma_f32_16x16x32_bf16 v[90:93], v[180:183], v[188:191], v[90:93]
	v_mfma_f32_16x16x32_bf16 v[86:89], v[160:163], v[196:199], v[86:89]
	v_mfma_f32_16x16x32_bf16 v[82:85], v[180:183], v[196:199], v[82:85]
	v_mfma_f32_16x16x32_bf16 v[78:81], v[160:163], v[204:207], v[78:81]
	v_mfma_f32_16x16x32_bf16 v[74:77], v[180:183], v[204:207], v[74:77]
	v_mfma_f32_16x16x32_bf16 v[70:73], v[160:163], v[212:215], v[70:73]
	v_mfma_f32_16x16x32_bf16 v[50:53], v[180:183], v[212:215], v[50:53]
	v_mfma_f32_16x16x32_bf16 v[94:97], v[176:179], v[192:195], v[94:97]
	v_mfma_f32_16x16x32_bf16 v[90:93], v[184:187], v[192:195], v[90:93]
	v_mfma_f32_16x16x32_bf16 v[86:89], v[176:179], v[200:203], v[86:89]
	v_mfma_f32_16x16x32_bf16 v[82:85], v[184:187], v[200:203], v[82:85]
	v_mfma_f32_16x16x32_bf16 v[78:81], v[176:179], v[208:211], v[78:81]
	v_mfma_f32_16x16x32_bf16 v[74:77], v[184:187], v[208:211], v[74:77]
	v_mfma_f32_16x16x32_bf16 v[70:73], v[176:179], v[230:233], v[70:73]
	v_mfma_f32_16x16x32_bf16 v[50:53], v[184:187], v[230:233], v[50:53]
	s_barrier
	s_add_i32 s62, s62, 2
	s_add_u32 s24, s24, 0x100
	s_addc_u32 s25, s25, 0
	s_add_u32 s60, s60, 0x100
	s_addc_u32 s61, s61, 0
